# fused diff-attn steady loop: issue the 3 LDS-DMA pieces from the MFMA gaps of the second PV block instead of between QK and rowmax
# baseline (speedup 1.0000x reference)
.LBB0_242:
	v_add_u32_e32 v0, s14, v254
	s_add_i32 s45, s14, 0xe800
	ds_read_b64_tr_b16 v[192:193], v0 offset:24576
	ds_read_b64_tr_b16 v[194:195], v0 offset:25088
	s_waitcnt lgkmcnt(9)
	v_mfma_f32_32x32x16_bf16 v[112:127], v[188:191], v[148:151], v[48:63]
	v_add_f32_e32 v2, v80, v81
	v_add_f32_e32 v2, v82, v2
	v_add_f32_e32 v2, v83, v2
	v_add_f32_e32 v2, v84, v2
	v_add_f32_e32 v2, v85, v2
	v_cvt_pk_bf16_f32 v156, v80, v81
	v_cvt_pk_bf16_f32 v157, v82, v83
	ds_read_b64_tr_b16 v[80:81], v0 offset:28672
	ds_read_b64_tr_b16 v[82:83], v0 offset:29184
	s_waitcnt lgkmcnt(10)
	v_mfma_f32_32x32x16_bf16 v[96:111], v[184:187], v[148:151], v[48:63]
	v_add_f32_e32 v2, v86, v2
	v_add_f32_e32 v2, v87, v2
	v_add_f32_e32 v2, v88, v2
	v_add_f32_e32 v6, v89, v2
	v_cvt_pk_bf16_f32 v158, v84, v85
	v_cvt_pk_bf16_f32 v159, v86, v87
	ds_read_b64_tr_b16 v[2:3], v0 offset:25600
	ds_read_b64_tr_b16 v[4:5], v0 offset:26112
	s_waitcnt lgkmcnt(11)
	v_mfma_f32_32x32x16_bf16 v[112:127], v[180:183], v[140:143], v[112:127]
	v_add_f32_e32 v6, v90, v6
	v_add_f32_e32 v6, v91, v6
	v_add_f32_e32 v6, v92, v6
	v_add_f32_e32 v10, v93, v6
	v_cvt_pk_bf16_f32 v152, v88, v89
	v_cvt_pk_bf16_f32 v153, v90, v91
	ds_read_b64_tr_b16 v[6:7], v0 offset:29696
	ds_read_b64_tr_b16 v[8:9], v0 offset:30208
	s_waitcnt lgkmcnt(12)
	v_mfma_f32_32x32x16_bf16 v[96:111], v[176:179], v[140:143], v[96:111]
	v_add_f32_e32 v10, v94, v10
	v_add_f32_e32 v10, v95, v10
	v_add_f32_e32 v10, v64, v10
	v_add_f32_e32 v14, v65, v10
	v_cvt_pk_bf16_f32 v154, v92, v93
	v_cvt_pk_bf16_f32 v155, v94, v95
	ds_read_b64_tr_b16 v[10:11], v0 offset:26624
	ds_read_b64_tr_b16 v[12:13], v0 offset:27136
	s_waitcnt lgkmcnt(13)
	v_mfma_f32_32x32x16_bf16 v[112:127], v[172:175], v[132:135], v[112:127]
	v_add_f32_e32 v14, v66, v14
	v_add_f32_e32 v14, v67, v14
	v_add_f32_e32 v14, v68, v14
	v_add_f32_e32 v14, v69, v14
	v_cvt_pk_bf16_f32 v144, v64, v65
	v_cvt_pk_bf16_f32 v145, v66, v67
	ds_read_b64_tr_b16 v[64:65], v0 offset:30720
	ds_read_b64_tr_b16 v[66:67], v0 offset:31232
	s_waitcnt lgkmcnt(14)
	v_mfma_f32_32x32x16_bf16 v[96:111], v[168:171], v[132:135], v[96:111]
	v_add_f32_e32 v14, v70, v14
	v_add_f32_e32 v14, v71, v14
	v_add_f32_e32 v14, v72, v14
	v_add_f32_e32 v14, v73, v14
	v_cvt_pk_bf16_f32 v146, v68, v69
	v_cvt_pk_bf16_f32 v147, v70, v71
	ds_read_b64_tr_b16 v[68:69], v0 offset:27648
	ds_read_b64_tr_b16 v[70:71], v0 offset:28160
	s_waitcnt lgkmcnt(14)
	v_mfma_f32_32x32x16_bf16 v[112:127], v[164:167], v[128:131], v[112:127]
	v_add_f32_e32 v14, v74, v14
	v_add_f32_e32 v14, v75, v14
	v_add_f32_e32 v14, v76, v14
	v_add_f32_e32 v14, v77, v14
	v_cvt_pk_bf16_f32 v136, v72, v73
	v_cvt_pk_bf16_f32 v137, v74, v75
	ds_read_b64_tr_b16 v[72:73], v0 offset:31744
	ds_read_b64_tr_b16 v[74:75], v0 offset:32256
	v_mfma_f32_32x32x16_bf16 v[96:111], v[160:163], v[128:131], v[96:111]
	v_add_f32_e32 v0, v78, v14
	v_add_f32_e32 v0, v79, v0
	v_add_f32_e32 v0, 0, v0
	v_cvt_pk_bf16_f32 v138, v76, v77
	v_cvt_pk_bf16_f32 v139, v78, v79
	s_nop 7
	v_max_f32_e32 v14, v113, v113
	v_max_f32_e32 v15, v112, v112
	v_max_f32_e32 v14, v15, v14
	v_max3_f32 v15, v114, v115, v97
	v_max3_f32 v14, v14, v96, v98
	v_max3_f32 v14, v14, v99, v116
	v_max3_f32 v15, v15, v118, v119
	v_max3_f32 v14, v14, v117, v100
	v_max3_f32 v15, v15, v102, v103
	v_max3_f32 v14, v14, v101, v120
	v_max3_f32 v15, v15, v122, v123
	v_max3_f32 v14, v14, v121, v104
	v_max3_f32 v15, v15, v106, v107
	v_max3_f32 v14, v14, v105, v124
	v_max3_f32 v15, v15, v126, v127
	v_max3_f32 v76, v14, v125, v108
	v_max3_f32 v15, v15, v110, v111
	v_add_f32_e32 v14, v224, v0
	v_max3_f32 v0, v76, v109, v15
	v_mov_b32_e32 v15, v0
	s_nop 1
	v_permlane32_swap_b32_e32 v0, v15
	v_max_f32_e32 v15, v15, v15
	v_max_f32_e32 v0, v0, v0
	v_max_f32_e32 v0, v0, v15
	v_cmp_lt_f32_e32 vcc, s91, v0
	s_cmp_lg_u64 vcc, 0
	s_cselect_b64 s[14:15], -1, 0
	s_cbranch_vccnz .LBB0_250
.LBB0_243:
	v_add_u32_e32 v0, s45, v254
	s_waitcnt lgkmcnt(14)
	v_mfma_f32_32x32x16_bf16 v[32:47], v[156:159], v[192:195], v[32:47]
	v_exp_f32_e32 v112, v112
	v_exp_f32_e32 v113, v113
	ds_read_b64_tr_b16 v[192:193], v0 offset:24576
	ds_read_b64_tr_b16 v[194:195], v0 offset:25088
	s_waitcnt lgkmcnt(14)
	v_mfma_f32_32x32x16_bf16 v[16:31], v[156:159], v[80:83], v[16:31]
	v_exp_f32_e32 v114, v114
	v_exp_f32_e32 v115, v115
	ds_read_b64_tr_b16 v[80:81], v0 offset:28672
	ds_read_b64_tr_b16 v[82:83], v0 offset:29184
	s_waitcnt lgkmcnt(14)
	v_mfma_f32_32x32x16_bf16 v[32:47], v[152:155], v[2:5], v[32:47]
	v_exp_f32_e32 v116, v116
	v_exp_f32_e32 v117, v117
	ds_read_b64_tr_b16 v[2:3], v0 offset:25600
	ds_read_b64_tr_b16 v[4:5], v0 offset:26112
	s_waitcnt lgkmcnt(14)
	v_mfma_f32_32x32x16_bf16 v[16:31], v[152:155], v[6:9], v[16:31]
	v_exp_f32_e32 v118, v118
	v_exp_f32_e32 v119, v119
	ds_read_b64_tr_b16 v[6:7], v0 offset:29696
	ds_read_b64_tr_b16 v[8:9], v0 offset:30208
	s_waitcnt lgkmcnt(14)
	v_mfma_f32_32x32x16_bf16 v[32:47], v[144:147], v[10:13], v[32:47]
	v_exp_f32_e32 v120, v120
	v_exp_f32_e32 v121, v121
	ds_read_b64_tr_b16 v[10:11], v0 offset:26624
	ds_read_b64_tr_b16 v[12:13], v0 offset:27136
	s_waitcnt lgkmcnt(14)
	v_mfma_f32_32x32x16_bf16 v[16:31], v[144:147], v[64:67], v[16:31]
	v_exp_f32_e32 v122, v122
	v_exp_f32_e32 v123, v123
	ds_read_b64_tr_b16 v[64:65], v0 offset:30720
	ds_read_b64_tr_b16 v[66:67], v0 offset:31232
	s_waitcnt lgkmcnt(14)
	v_mfma_f32_32x32x16_bf16 v[32:47], v[136:139], v[68:71], v[32:47]
	v_exp_f32_e32 v124, v124
	v_exp_f32_e32 v125, v125
	ds_read_b64_tr_b16 v[68:69], v0 offset:27648
	ds_read_b64_tr_b16 v[70:71], v0 offset:28160
	s_waitcnt lgkmcnt(14)
	v_mfma_f32_32x32x16_bf16 v[16:31], v[136:139], v[72:75], v[16:31]
	v_exp_f32_e32 v126, v126
	v_exp_f32_e32 v127, v127
	ds_read_b64_tr_b16 v[72:73], v0 offset:31744
	ds_read_b64_tr_b16 v[74:75], v0 offset:32256
	s_waitcnt lgkmcnt(14)
	v_mfma_f32_32x32x16_bf16 v[226:241], v[156:159], v[192:195], v[226:241]
	v_exp_f32_e32 v96, v96
	v_exp_f32_e32 v97, v97
	s_waitcnt lgkmcnt(12)
	v_mfma_f32_32x32x16_bf16 v[208:223], v[156:159], v[80:83], v[208:223]
	v_exp_f32_e32 v98, v98
	v_exp_f32_e32 v99, v99
	v_lshl_add_u64 v[80:81], v[202:203], 0, s[86:87]
	s_add_i32 s46, s22, s38
	s_mov_b32 s47, m0
	s_mov_b32 m0, s46
	s_nop 0
	global_load_lds_dwordx4 v[80:81], off
	v_add_u32_e32 v0, s20, v253
	ds_read_b128 v[76:79], v0
	ds_read_b128 v[184:187], v0 offset:512
	s_waitcnt lgkmcnt(12)
	v_mfma_f32_32x32x16_bf16 v[226:241], v[152:155], v[2:5], v[226:241]
	v_exp_f32_e32 v100, v100
	v_exp_f32_e32 v101, v101
	v_lshl_add_u64 v[80:81], v[200:201], 0, s[86:87]
	s_add_i32 s46, s20, s39
	s_mov_b32 m0, s46
	s_nop 0
	global_load_lds_dwordx4 v[80:81], off
	ds_read_b128 v[188:191], v0 offset:2048
	ds_read_b128 v[180:183], v0 offset:2560
	s_waitcnt lgkmcnt(12)
	v_mfma_f32_32x32x16_bf16 v[208:223], v[152:155], v[6:9], v[208:223]
	v_exp_f32_e32 v102, v102
	v_exp_f32_e32 v103, v103
	s_add_i32 s46, s46, 0xe780
	s_mov_b32 m0, s46
	s_nop 0
	global_load_lds_dwordx4 v[80:81], off offset:128
	s_mov_b32 m0, s47
	ds_read_b128 v[176:179], v0 offset:4096
	ds_read_b128 v[172:175], v0 offset:4608
	s_waitcnt lgkmcnt(12)
	v_mfma_f32_32x32x16_bf16 v[226:241], v[144:147], v[10:13], v[226:241]
	v_exp_f32_e32 v104, v104
	v_exp_f32_e32 v105, v105
	ds_read_b128 v[168:171], v0 offset:6144
	ds_read_b128 v[164:167], v0 offset:6656
	s_waitcnt lgkmcnt(12)
	v_mfma_f32_32x32x16_bf16 v[208:223], v[144:147], v[64:67], v[208:223]
	v_exp_f32_e32 v106, v106
	v_exp_f32_e32 v107, v107
	s_waitcnt lgkmcnt(10)
	v_mfma_f32_32x32x16_bf16 v[226:241], v[136:139], v[68:71], v[226:241]
	v_exp_f32_e32 v108, v108
	v_exp_f32_e32 v109, v109
	s_waitcnt lgkmcnt(8)
	v_mfma_f32_32x32x16_bf16 v[208:223], v[136:139], v[72:75], v[208:223]
	v_exp_f32_e32 v110, v110
	v_exp_f32_e32 v111, v111
	s_waitcnt vmcnt(3) lgkmcnt(0)
	s_barrier
	s_andn2_b64 vcc, exec, s[14:15]
	v_add_u32_e32 v0, s37, v255
	s_cbranch_vccnz .LBB0_245
	s_waitcnt lgkmcnt(0)
	ds_read_b128 v[2:5], v0 offset:49248
	ds_read_b128 v[6:9], v0 offset:49216
	ds_read_b128 v[10:13], v0 offset:49184
	ds_read_b128 v[64:67], v0 offset:49152
	s_waitcnt lgkmcnt(3)
	v_pk_mul_f32 v[44:45], v[44:45], v[2:3]
	s_waitcnt lgkmcnt(2)
	v_pk_mul_f32 v[40:41], v[40:41], v[6:7]
	s_waitcnt lgkmcnt(1)
	v_pk_mul_f32 v[36:37], v[36:37], v[10:11]
	v_pk_mul_f32 v[46:47], v[46:47], v[4:5]
	v_pk_mul_f32 v[42:43], v[42:43], v[8:9]
	v_pk_mul_f32 v[38:39], v[38:39], v[12:13]
	s_waitcnt lgkmcnt(0)
	v_pk_mul_f32 v[34:35], v[34:35], v[66:67]
	v_pk_mul_f32 v[32:33], v[32:33], v[64:65]
	v_pk_mul_f32 v[28:29], v[28:29], v[2:3]
	v_pk_mul_f32 v[24:25], v[24:25], v[6:7]
	v_pk_mul_f32 v[20:21], v[20:21], v[10:11]
	v_pk_mul_f32 v[30:31], v[30:31], v[4:5]
	v_pk_mul_f32 v[26:27], v[26:27], v[8:9]
	v_pk_mul_f32 v[22:23], v[22:23], v[12:13]
	v_pk_mul_f32 v[18:19], v[18:19], v[66:67]
	v_pk_mul_f32 v[16:17], v[16:17], v[64:65]
	v_pk_mul_f32 v[238:239], v[238:239], v[2:3]
	v_pk_mul_f32 v[234:235], v[234:235], v[6:7]
	v_pk_mul_f32 v[230:231], v[230:231], v[10:11]
	v_pk_mul_f32 v[240:241], v[240:241], v[4:5]
	v_pk_mul_f32 v[236:237], v[236:237], v[8:9]
	v_pk_mul_f32 v[232:233], v[232:233], v[12:13]
	v_pk_mul_f32 v[228:229], v[228:229], v[66:67]
	v_pk_mul_f32 v[226:227], v[226:227], v[64:65]
	v_pk_mul_f32 v[220:221], v[220:221], v[2:3]
	v_pk_mul_f32 v[216:217], v[216:217], v[6:7]
	v_pk_mul_f32 v[212:213], v[212:213], v[10:11]
	v_pk_mul_f32 v[222:223], v[222:223], v[4:5]
	v_pk_mul_f32 v[218:219], v[218:219], v[8:9]
	v_pk_mul_f32 v[214:215], v[214:215], v[12:13]
	v_pk_mul_f32 v[210:211], v[210:211], v[66:67]
	v_pk_mul_f32 v[208:209], v[208:209], v[64:65]
.LBB0_245:
	s_add_i32 s14, s20, 0x2000
	s_cmpk_lg_i32 s20, 0x4000
	s_cselect_b32 s41, s14, 0
	v_add_u32_e32 v15, s22, v254
	s_add_i32 s45, s22, 0xe800
	ds_read_b64_tr_b16 v[160:161], v15 offset:24576
	ds_read_b64_tr_b16 v[162:163], v15 offset:25088
	s_waitcnt lgkmcnt(9)
	v_mfma_f32_32x32x16_bf16 v[80:95], v[76:79], v[148:151], v[48:63]
	v_add_f32_e32 v2, v112, v113
	v_add_f32_e32 v2, v114, v2
	v_add_f32_e32 v2, v115, v2
	v_add_f32_e32 v2, v116, v2
	v_add_f32_e32 v2, v117, v2
	v_cvt_pk_bf16_f32 v156, v112, v113
	v_cvt_pk_bf16_f32 v157, v114, v115
	ds_read_b64_tr_b16 v[112:113], v15 offset:28672
	ds_read_b64_tr_b16 v[114:115], v15 offset:29184
	s_waitcnt lgkmcnt(10)
	v_mfma_f32_32x32x16_bf16 v[64:79], v[184:187], v[148:151], v[48:63]
	v_add_f32_e32 v2, v118, v2
	v_add_f32_e32 v2, v119, v2
	v_add_f32_e32 v2, v120, v2
	v_add_f32_e32 v6, v121, v2
	v_cvt_pk_bf16_f32 v158, v116, v117
	v_cvt_pk_bf16_f32 v159, v118, v119
	ds_read_b64_tr_b16 v[2:3], v15 offset:25600
	ds_read_b64_tr_b16 v[4:5], v15 offset:26112
	s_waitcnt lgkmcnt(11)
	v_mfma_f32_32x32x16_bf16 v[80:95], v[188:191], v[140:143], v[80:95]
	v_add_f32_e32 v6, v122, v6
	v_add_f32_e32 v6, v123, v6
	v_add_f32_e32 v6, v124, v6
	v_add_f32_e32 v10, v125, v6
	v_cvt_pk_bf16_f32 v152, v120, v121
	v_cvt_pk_bf16_f32 v153, v122, v123
	ds_read_b64_tr_b16 v[6:7], v15 offset:29696
	ds_read_b64_tr_b16 v[8:9], v15 offset:30208
	s_waitcnt lgkmcnt(12)
	v_mfma_f32_32x32x16_bf16 v[64:79], v[180:183], v[140:143], v[64:79]
	v_add_f32_e32 v10, v126, v10
	v_add_f32_e32 v10, v127, v10
	v_add_f32_e32 v10, v96, v10
	v_add_f32_e32 v116, v97, v10
	v_cvt_pk_bf16_f32 v154, v124, v125
	v_cvt_pk_bf16_f32 v155, v126, v127
	ds_read_b64_tr_b16 v[10:11], v15 offset:26624
	ds_read_b64_tr_b16 v[12:13], v15 offset:27136
	s_waitcnt lgkmcnt(13)
	v_mfma_f32_32x32x16_bf16 v[80:95], v[176:179], v[132:135], v[80:95]
	v_add_f32_e32 v116, v98, v116
	v_add_f32_e32 v116, v99, v116
	v_add_f32_e32 v116, v100, v116
	v_add_f32_e32 v116, v101, v116
	v_cvt_pk_bf16_f32 v144, v96, v97
	v_cvt_pk_bf16_f32 v145, v98, v99
	ds_read_b64_tr_b16 v[96:97], v15 offset:30720
	ds_read_b64_tr_b16 v[98:99], v15 offset:31232
	s_waitcnt lgkmcnt(14)
	v_mfma_f32_32x32x16_bf16 v[64:79], v[172:175], v[132:135], v[64:79]
	v_add_f32_e32 v116, v102, v116
	v_add_f32_e32 v116, v103, v116
	v_add_f32_e32 v116, v104, v116
	v_add_f32_e32 v116, v105, v116
	v_cvt_pk_bf16_f32 v146, v100, v101
	v_cvt_pk_bf16_f32 v147, v102, v103
	ds_read_b64_tr_b16 v[100:101], v15 offset:27648
	ds_read_b64_tr_b16 v[102:103], v15 offset:28160
	s_waitcnt lgkmcnt(14)
	v_mfma_f32_32x32x16_bf16 v[80:95], v[168:171], v[128:131], v[80:95]
	v_add_f32_e32 v116, v106, v116
	v_add_f32_e32 v116, v107, v116
	v_add_f32_e32 v116, v108, v116
	v_add_f32_e32 v116, v109, v116
	v_cvt_pk_bf16_f32 v136, v104, v105
	v_cvt_pk_bf16_f32 v137, v106, v107
	ds_read_b64_tr_b16 v[104:105], v15 offset:31744
	ds_read_b64_tr_b16 v[106:107], v15 offset:32256
	v_mfma_f32_32x32x16_bf16 v[64:79], v[164:167], v[128:131], v[64:79]
	v_add_f32_e32 v15, v110, v116
	v_add_f32_e32 v15, v111, v15
	v_add_f32_e32 v15, 0, v15
	v_cvt_pk_bf16_f32 v138, v108, v109
	v_cvt_pk_bf16_f32 v139, v110, v111
	v_max_f32_e32 v108, v81, v81
	v_max_f32_e32 v109, v80, v80
	v_max_f32_e32 v108, v109, v108
	s_nop 3
	v_max3_f32 v109, v82, v83, v65
	v_max3_f32 v108, v108, v64, v66
	v_max3_f32 v108, v108, v67, v84
	v_max3_f32 v109, v109, v86, v87
	v_max3_f32 v108, v108, v85, v68
	v_max3_f32 v109, v109, v70, v71
	v_max3_f32 v108, v108, v69, v88
	v_max3_f32 v109, v109, v90, v91
	v_max3_f32 v108, v108, v89, v72
	v_max3_f32 v109, v109, v74, v75
	v_max3_f32 v108, v108, v73, v92
	v_max3_f32 v109, v109, v94, v95
	v_max3_f32 v108, v108, v93, v76
	v_max3_f32 v109, v109, v78, v79
	v_add_f32_e32 v224, v14, v15
	v_max3_f32 v14, v108, v77, v109
	v_mov_b32_e32 v15, v14
	s_nop 1
	v_permlane32_swap_b32_e32 v14, v15
	v_max_f32_e32 v15, v15, v15
	v_max_f32_e32 v14, v14, v14
	v_max_f32_e32 v14, v14, v15
	v_cmp_lt_f32_e32 vcc, s91, v14
	s_cmp_lg_u64 vcc, 0
	s_cselect_b64 s[14:15], -1, 0
	s_cbranch_vccnz .LBB0_253
.LBB0_246:
	v_add_u32_e32 v14, s45, v254
	s_waitcnt lgkmcnt(14)
	v_mfma_f32_32x32x16_bf16 v[32:47], v[156:159], v[160:163], v[32:47]
	v_exp_f32_e32 v80, v80
	v_exp_f32_e32 v81, v81
	ds_read_b64_tr_b16 v[160:161], v14 offset:24576
	ds_read_b64_tr_b16 v[162:163], v14 offset:25088
	s_waitcnt lgkmcnt(14)
	v_mfma_f32_32x32x16_bf16 v[16:31], v[156:159], v[112:115], v[16:31]
	v_exp_f32_e32 v82, v82
	v_exp_f32_e32 v83, v83
	ds_read_b64_tr_b16 v[112:113], v14 offset:28672
	ds_read_b64_tr_b16 v[114:115], v14 offset:29184
	s_waitcnt lgkmcnt(14)
	v_mfma_f32_32x32x16_bf16 v[32:47], v[152:155], v[2:5], v[32:47]
	v_exp_f32_e32 v84, v84
	v_exp_f32_e32 v85, v85
	ds_read_b64_tr_b16 v[2:3], v14 offset:25600
	ds_read_b64_tr_b16 v[4:5], v14 offset:26112
	s_waitcnt lgkmcnt(14)
	v_mfma_f32_32x32x16_bf16 v[16:31], v[152:155], v[6:9], v[16:31]
	v_exp_f32_e32 v86, v86
	v_exp_f32_e32 v87, v87
	ds_read_b64_tr_b16 v[6:7], v14 offset:29696
	ds_read_b64_tr_b16 v[8:9], v14 offset:30208
	s_waitcnt lgkmcnt(14)
	v_mfma_f32_32x32x16_bf16 v[32:47], v[144:147], v[10:13], v[32:47]
	v_exp_f32_e32 v88, v88
	v_exp_f32_e32 v89, v89
	ds_read_b64_tr_b16 v[10:11], v14 offset:26624
	ds_read_b64_tr_b16 v[12:13], v14 offset:27136
	s_waitcnt lgkmcnt(14)
	v_mfma_f32_32x32x16_bf16 v[16:31], v[144:147], v[96:99], v[16:31]
	v_exp_f32_e32 v90, v90
	v_exp_f32_e32 v91, v91
	ds_read_b64_tr_b16 v[96:97], v14 offset:30720
	ds_read_b64_tr_b16 v[98:99], v14 offset:31232
	s_waitcnt lgkmcnt(14)
	v_mfma_f32_32x32x16_bf16 v[32:47], v[136:139], v[100:103], v[32:47]
	v_exp_f32_e32 v92, v92
	v_exp_f32_e32 v93, v93
	ds_read_b64_tr_b16 v[100:101], v14 offset:27648
	ds_read_b64_tr_b16 v[102:103], v14 offset:28160
	s_waitcnt lgkmcnt(14)
	v_mfma_f32_32x32x16_bf16 v[16:31], v[136:139], v[104:107], v[16:31]
	v_exp_f32_e32 v94, v94
	v_exp_f32_e32 v95, v95
	ds_read_b64_tr_b16 v[104:105], v14 offset:31744
	ds_read_b64_tr_b16 v[106:107], v14 offset:32256
	s_waitcnt lgkmcnt(14)
	v_mfma_f32_32x32x16_bf16 v[226:241], v[156:159], v[160:163], v[226:241]
	v_exp_f32_e32 v64, v64
	v_exp_f32_e32 v65, v65
	s_waitcnt lgkmcnt(12)
	v_mfma_f32_32x32x16_bf16 v[208:223], v[156:159], v[112:115], v[208:223]
	v_exp_f32_e32 v66, v66
	v_exp_f32_e32 v67, v67
	s_add_i32 s46, s20, s38
	s_mov_b32 s47, m0
	s_mov_b32 m0, s46
	s_nop 0
	global_load_lds_dwordx4 v[202:203], off
	v_add_u32_e32 v14, s41, v253
	ds_read_b128 v[188:191], v14
	ds_read_b128 v[184:187], v14 offset:512
	s_waitcnt lgkmcnt(12)
	v_mfma_f32_32x32x16_bf16 v[226:241], v[152:155], v[2:5], v[226:241]
	v_exp_f32_e32 v68, v68
	v_exp_f32_e32 v69, v69
	s_add_i32 s46, s41, s39
	s_mov_b32 m0, s46
	s_nop 0
	global_load_lds_dwordx4 v[200:201], off
	ds_read_b128 v[180:183], v14 offset:2048
	ds_read_b128 v[176:179], v14 offset:2560
	s_waitcnt lgkmcnt(12)
	v_mfma_f32_32x32x16_bf16 v[208:223], v[152:155], v[6:9], v[208:223]
	v_exp_f32_e32 v70, v70
	v_exp_f32_e32 v71, v71
	s_add_i32 s46, s46, 0xe780
	s_mov_b32 m0, s46
	s_nop 0
	global_load_lds_dwordx4 v[200:201], off offset:128
	s_mov_b32 m0, s47
	ds_read_b128 v[172:175], v14 offset:4096
	ds_read_b128 v[168:171], v14 offset:4608
	s_waitcnt lgkmcnt(12)
	v_mfma_f32_32x32x16_bf16 v[226:241], v[144:147], v[10:13], v[226:241]
	v_exp_f32_e32 v72, v72
	v_exp_f32_e32 v73, v73
	ds_read_b128 v[164:167], v14 offset:6144
	ds_read_b128 v[160:163], v14 offset:6656
	s_waitcnt lgkmcnt(12)
	v_mfma_f32_32x32x16_bf16 v[208:223], v[144:147], v[96:99], v[208:223]
	v_exp_f32_e32 v74, v74
	v_exp_f32_e32 v75, v75
	s_waitcnt lgkmcnt(10)
	v_mfma_f32_32x32x16_bf16 v[226:241], v[136:139], v[100:103], v[226:241]
	v_exp_f32_e32 v76, v76
	v_exp_f32_e32 v77, v77
	s_waitcnt lgkmcnt(8)
	v_mfma_f32_32x32x16_bf16 v[208:223], v[136:139], v[104:107], v[208:223]
	v_exp_f32_e32 v78, v78
	v_exp_f32_e32 v79, v79
	s_waitcnt vmcnt(3) lgkmcnt(0)
	s_barrier
	s_andn2_b64 vcc, exec, s[14:15]
	s_cbranch_vccnz .LBB0_248
	s_waitcnt lgkmcnt(0)
	ds_read_b128 v[2:5], v0 offset:49248
	ds_read_b128 v[6:9], v0 offset:49216
	ds_read_b128 v[10:13], v0 offset:49184
	ds_read_b128 v[96:99], v0 offset:49152
	s_waitcnt lgkmcnt(3)
	v_pk_mul_f32 v[44:45], v[44:45], v[2:3]
	s_waitcnt lgkmcnt(2)
	v_pk_mul_f32 v[40:41], v[40:41], v[6:7]
	s_waitcnt lgkmcnt(1)
	v_pk_mul_f32 v[36:37], v[36:37], v[10:11]
	v_pk_mul_f32 v[46:47], v[46:47], v[4:5]
	v_pk_mul_f32 v[42:43], v[42:43], v[8:9]
	v_pk_mul_f32 v[38:39], v[38:39], v[12:13]
	s_waitcnt lgkmcnt(0)
	v_pk_mul_f32 v[34:35], v[34:35], v[98:99]
	v_pk_mul_f32 v[32:33], v[32:33], v[96:97]
	v_pk_mul_f32 v[28:29], v[28:29], v[2:3]
	v_pk_mul_f32 v[24:25], v[24:25], v[6:7]
	v_pk_mul_f32 v[20:21], v[20:21], v[10:11]
	v_pk_mul_f32 v[30:31], v[30:31], v[4:5]
	v_pk_mul_f32 v[26:27], v[26:27], v[8:9]
	v_pk_mul_f32 v[22:23], v[22:23], v[12:13]
	v_pk_mul_f32 v[18:19], v[18:19], v[98:99]
	v_pk_mul_f32 v[16:17], v[16:17], v[96:97]
	v_pk_mul_f32 v[238:239], v[238:239], v[2:3]
	v_pk_mul_f32 v[234:235], v[234:235], v[6:7]
	v_pk_mul_f32 v[230:231], v[230:231], v[10:11]
	v_pk_mul_f32 v[240:241], v[240:241], v[4:5]
	v_pk_mul_f32 v[236:237], v[236:237], v[8:9]
	v_pk_mul_f32 v[232:233], v[232:233], v[12:13]
	v_pk_mul_f32 v[228:229], v[228:229], v[98:99]
	v_pk_mul_f32 v[226:227], v[226:227], v[96:97]
	v_pk_mul_f32 v[220:221], v[220:221], v[2:3]
	v_pk_mul_f32 v[216:217], v[216:217], v[6:7]
	v_pk_mul_f32 v[212:213], v[212:213], v[10:11]
	v_pk_mul_f32 v[222:223], v[222:223], v[4:5]
	v_pk_mul_f32 v[218:219], v[218:219], v[8:9]
	v_pk_mul_f32 v[214:215], v[214:215], v[12:13]
	v_pk_mul_f32 v[210:211], v[210:211], v[98:99]
	v_pk_mul_f32 v[208:209], v[208:209], v[96:97]
